# one static s_setprio 1 for waves 4..7 per GEMM phase (per-block flips already removed), reset to 0 after the phase
# baseline (speedup 1.0000x reference)
.LBB0_84:
	s_cmp_lt_i32 s92, 0
	s_cbranch_scc1 .LBB0_168
	s_cmp_ge_u32 s29, 0x100
	s_cbranch_scc0 .Lsp1_done
	s_setprio 1
.Lsp1_done:
	v_readlane_b32 s0, v253, 55
	v_mbcnt_lo_u32_b32 v2, -1, 0
	v_mbcnt_hi_u32_b32 v2, -1, v2
	v_readlane_b32 s1, v253, 56
	v_add_u32_e32 v1, s29, v2
	s_andn2_b64 vcc, exec, s[0:1]
	v_readfirstlane_b32 s4, v1
	s_cbranch_vccnz .LBB0_169
	v_lshlrev_b32_e32 v4, 4, v1
	v_add_u32_e32 v0, 0x2000, v4
	v_ashrrev_i32_e32 v5, 31, v0
	v_lshrrev_b32_e32 v5, 22, v5
	s_mov_b32 s0, s92
	v_add_u32_e32 v5, v0, v5
	v_writelane_b32 v255, s0, 13
	v_ashrrev_i32_e32 v12, 10, v5
	s_cmp_eq_u32 s92, 1
	v_writelane_b32 v255, s1, 14
	s_movk_i32 s0, 0xa0
	v_mul_i32_i24_e32 v5, 0x400, v12
	s_cselect_b32 s0, s0, 0xa8
	s_brev_b32 s1, 16
	v_sub_u32_e32 v0, v0, v5
	s_cselect_b32 s5, s1, 0x14e0000
	s_add_u32 s0, s88, s0
	v_lshrrev_b32_e32 v5, 4, v0
	s_addc_u32 s1, s89, 0
	v_bitop3_b32 v0, v5, v0, 32 bitop3:0x6c
	s_load_dwordx2 s[0:1], s[0:1], 0x0
	s_nop 0
	s_load_dwordx2 s[92:93], s[88:89], 0xa8
	v_ashrrev_i32_e32 v5, 31, v0
	v_lshrrev_b32_e32 v5, 26, v5
	v_add_u32_e32 v5, v0, v5
	v_lshlrev_b32_e32 v6, 3, v12
	v_ashrrev_i32_e32 v13, 6, v5
	v_and_b32_e32 v6, -16, v6
	s_waitcnt lgkmcnt(0)
	s_add_u32 s96, s0, s5
	v_add_u32_e32 v6, v13, v6
	s_addc_u32 s70, s1, 0
	v_and_b32_e32 v7, 3, v13
	s_mov_b32 s1, 0x1fffe0
	v_lshrrev_b32_e32 v8, 2, v6
	v_lshlrev_b32_e32 v9, 1, v6
	v_and_b32_e32 v5, 0xc0, v5
	v_and_or_b32 v7, v6, s1, v7
	v_and_b32_e32 v8, 4, v8
	v_and_b32_e32 v9, 24, v9
	v_sub_u32_e32 v0, v0, v5
	v_or3_b32 v7, v7, v8, v9
	v_lshlrev_b32_e32 v8, 5, v12
	v_ashrrev_i16_sdwa v0, v240, sext(v0) dst_sel:DWORD dst_unused:UNUSED_PAD src0_sel:DWORD src1_sel:BYTE_0
	v_and_b32_e32 v8, 32, v8
	v_bfe_i32 v14, v0, 0, 16
	v_add_lshl_u32 v5, v8, v14, 1
	v_lshl_add_u32 v0, v7, 11, v5
	v_lshl_add_u32 v148, v6, 11, v5
	v_bfe_i32 v5, v1, 27, 1
	v_lshrrev_b32_e32 v5, 22, v5
	v_add_u32_e32 v5, v4, v5
	v_and_b32_e32 v5, 0xfffffc00, v5
	v_sub_u32_e32 v4, v4, v5
	v_lshrrev_b32_e32 v5, 4, v4
	v_ashrrev_i32_e32 v6, 31, v1
	v_bitop3_b32 v4, v5, v4, 32 bitop3:0x6c
	v_lshrrev_b32_e32 v6, 26, v6
	v_ashrrev_i32_e32 v5, 31, v4
	v_add_u32_e32 v1, v1, v6
	v_lshrrev_b32_e32 v5, 26, v5
	v_ashrrev_i32_e32 v16, 6, v1
	v_add_u32_e32 v5, v4, v5
	v_lshlrev_b32_e32 v1, 3, v16
	v_ashrrev_i32_e32 v15, 6, v5
	v_and_b32_e32 v1, -16, v1
	v_add_u32_e32 v1, v15, v1
	v_and_b32_e32 v6, 3, v15
	v_lshrrev_b32_e32 v7, 2, v1
	v_lshlrev_b32_e32 v8, 1, v1
	v_and_b32_e32 v5, 0xc0, v5
	s_ashr_i32 s0, s4, 6
	v_and_or_b32 v6, v1, s1, v6
	v_and_b32_e32 v7, 4, v7
	v_and_b32_e32 v8, 24, v8
	v_sub_u32_e32 v4, v4, v5
	s_ashr_i32 s71, s4, 8
	s_lshl_b32 s72, s0, 10
	v_or3_b32 v6, v6, v7, v8
	v_lshlrev_b32_e32 v7, 5, v16
	v_ashrrev_i16_sdwa v4, v240, sext(v4) dst_sel:DWORD dst_unused:UNUSED_PAD src0_sel:DWORD src1_sel:BYTE_0
	v_readlane_b32 s6, v254, 22
	v_and_b32_e32 v7, 32, v7
	v_bfe_i32 v17, v4, 0, 16
	v_readlane_b32 s7, v254, 23
	s_add_u32 s60, s92, s6
	v_add_lshl_u32 v4, v7, v17, 1
	s_addc_u32 s61, s93, s7
	s_add_i32 s73, s72, 0
	v_lshl_add_u32 v150, v6, 11, v4
	s_add_i32 m0, s73, 0x10000
	v_lshl_add_u32 v152, v1, 11, v4
	global_load_lds_dwordx4 v150, s[60:61]
	s_add_i32 m0, s73, 0x12000
	s_add_u32 s6, s60, 0x40000
	global_load_lds_dwordx4 v0, s[60:61]
	s_addc_u32 s7, s61, 0
	s_add_i32 m0, s73, 0x14000
	v_writelane_b32 v255, s88, 15
	global_load_lds_dwordx4 v150, s[6:7]
	s_add_i32 m0, s73, 0x16000
	s_load_dwordx4 s[52:55], s[88:89], 0x28
	global_load_lds_dwordx4 v0, s[6:7]
	v_readlane_b32 s6, v254, 40
	v_readlane_b32 s7, v254, 41
	s_add_u32 s48, s96, s6
	s_addc_u32 s49, s70, s7
	s_add_i32 s74, s73, 0x2000
	s_mov_b32 m0, s73
	s_add_u32 s6, s48, 0x40000
	global_load_lds_dwordx4 v152, s[48:49]
	s_mov_b32 m0, s74
	s_addc_u32 s7, s49, 0
	s_add_i32 s75, s73, 0x4000
	global_load_lds_dwordx4 v148, s[48:49]
	s_mov_b32 m0, s75
	s_add_i32 s76, s73, 0x6000
	global_load_lds_dwordx4 v152, s[6:7]
	s_mov_b32 m0, s76
	v_mov_b32_e32 v151, v3
	global_load_lds_dwordx4 v148, s[6:7]
	v_mov_b32_e32 v1, v3
	v_mov_b32_e32 v153, v3
	v_mov_b32_e32 v149, v3
	s_cmp_eq_u32 s71, 1
	v_writelane_b32 v255, s89, 16
	v_lshl_add_u64 v[10:11], s[60:61], 0, v[150:151]
	v_lshl_add_u64 v[8:9], s[60:61], 0, v[0:1]
	v_lshl_add_u64 v[4:5], s[48:49], 0, v[152:153]
	s_cselect_b64 s[34:35], -1, 0
	s_cmp_lg_u32 s71, 1
	v_lshl_add_u64 v[6:7], s[48:49], 0, v[148:149]
	s_cbranch_scc1 .LBB0_88
	s_barrier

.LBB0_171:
	s_setprio 0
	s_and_b64 s[0:1], s[0:1], exec
	s_cselect_b32 s10, 64, 0
	s_cmp_eq_u32 s92, 2
	s_cselect_b64 s[0:1], -1, 0
	s_cmp_lt_i32 s86, s10
	s_cselect_b64 s[4:5], -1, 0
	s_or_b64 s[0:1], s[0:1], s[4:5]
	s_and_b64 vcc, exec, s[0:1]
	s_cbranch_vccnz .LBB0_188
	v_add_co_u32_e64 v0, s[0:1], s92, 1
	s_mov_b64 s[8:9], s[88:89]
	v_mbcnt_lo_u32_b32 v1, -1, 0
	v_mbcnt_hi_u32_b32 v1, -1, v1
	s_andn2_b64 vcc, exec, s[0:1]
	v_add_u32_e32 v2, s29, v1
	s_mov_b64 s[4:5], -1
	s_cbranch_vccz .LBB0_174
	s_load_dwordx2 s[0:1], s[8:9], 0x8
	s_ashr_i32 s93, s92, 31
	s_lshl_b64 s[4:5], s[92:93], 26
	s_waitcnt lgkmcnt(0)
	s_add_u32 s0, s0, s4
	s_addc_u32 s1, s1, s5
	s_mov_b64 s[4:5], 0

.LBB0_668:
	s_or_b64 exec, exec, s[0:1]
	s_waitcnt lgkmcnt(0)
	s_barrier
	s_cmp_ge_u32 s29, 0x100
	s_cbranch_scc0 .Lsp2_done
	s_setprio 1
.Lsp2_done:
	s_load_dwordx4 s[44:47], s[88:89], 0xa0
	v_readlane_b32 s0, v255, 9
	v_readlane_b32 s1, v255, 10
	s_mov_b64 s[4:5], -1
	s_and_b64 vcc, exec, s[0:1]
	s_cbranch_vccz .LBB0_670
	s_load_dwordx2 s[0:1], s[88:89], 0x0
	s_mov_b64 s[4:5], 0

.LBB0_692:
	s_setprio 0
	s_waitcnt vmcnt(0)
	s_waitcnt lgkmcnt(0)
	s_barrier
	s_and_saveexec_b64 s[0:1], s[90:91]
	s_xor_b64 s[0:1], exec, s[0:1]
	s_cbranch_execz .LBB0_745
	v_readlane_b32 s4, v254, 32
	s_waitcnt vmcnt(0) expcnt(0) lgkmcnt(0)
	s_nop 0
	v_mov_b32_e32 v0, s4
	ds_read_b32 v2, v0
	v_readlane_b32 s4, v254, 33
	s_waitcnt lgkmcnt(0)
	v_cmp_ne_u32_e32 vcc, 0, v2
	v_mov_b32_e32 v0, s4
	ds_read_b32 v0, v0
	s_cbranch_vccnz .LBB0_708
	s_mov_b32 s10, 1
	s_branch .LBB0_696
